# prep_item: prefetch next item's P loads and lb table one item ahead, drop redundant vmcnt waits
# speedup vs baseline: 1.0111x; 1.0111x over previous
; #define LAS __attribute__((address_space(3)))
; __device__ __forceinline__ size_t PIX(int row, int col) { return (size_t)(col >> 7) * PSLOT + (size_t)row * 128 + (col & 127); }
; __device__ void prep_item(const Params& p, int l, int item, LAS unsigned char* lds) {
;     ...
;     const int ci = item % NCH, bh = item / NCH, h = bh & 3, b = bh >> 2;
;     const int R0 = ci < 8 ? NLAT + b * 256 + 32 * ci : b * 4096 + 32 * (ci - 8);
;     bf16_t* P = (bf16_t*)(p.ws + WS_BIG);
;     const bool first = (l == 0);
;     const bool want_out = first || ci >= 8;
;     for (int dd = 0; dd < 2; ++dd) { LAS unsigned* az = (LAS unsigned*)(lds + dd * P1_DIRSZ + P1_AW) + w * (32 * KT_ST / 2); for (int i = lane; i < 32 * KT_ST / 2; i += 64) az[i] = 0u; }
;     u32x4 rf0, rq0, rv0, rf1, rq1, rv1;
;     { const int r_ = R0 + tau; rf0 = *(const u32x4*)(P + PIX(r_, h * 128 + k0)); rq0 = *(const u32x4*)(P + PIX(r_, 1536 + h * 128 + k0)); rv0 = *(const u32x4*)(P + PIX(r_, 1024 + h * 128 + k0)); }
;     { const int r_ = R0 + 31 - tau; rf1 = *(const u32x4*)(P + PIX(r_, 512 + h * 128 + k0)); rq1 = *(const u32x4*)(P + PIX(r_, 1536 + h * 128 + k0)); rv1 = *(const u32x4*)(P + PIX(r_, 1024 + h * 128 + k0)); }
;     asm volatile("s_waitcnt vmcnt(0)" ::: "memory");
;     __syncthreads();
;     auto valu_part = [&](const int dir, const u32x4& f, const u32x4& q, const u32x4& v) {
;         LAS unsigned char* db = lds + dir * P1_DIRSZ;
;         LAS bf16_t* Qs = (LAS bf16_t*)(db + P1_QS); LAS bf16_t* Kh = (LAS bf16_t*)(db + P1_KH);
;         LAS bf16_t* Vt = (LAS bf16_t*)(db + P1_VT); LAS bf16_t* Kt = (LAS bf16_t*)(db + P1_KT);
;         LAS bf16_t* Aw = (LAS bf16_t*)(db + P1_AW) + w * 32 * KT_ST;
;         const int tokl = dir ? 31 - tau : tau;
;         const float* lbp = (const float*)(p.ws + WS_LB) + dir * 512 + h * 128 + k0;
.LBB0_240:
	s_or_b64 exec, exec, s[0:1]
	v_readlane_b32 s0, v243, 41
	v_readlane_b32 s1, v243, 42
	s_andn2_b64 vcc, exec, s[0:1]
	s_waitcnt lgkmcnt(0)
	s_barrier
	s_cbranch_vccnz .LBB0_319
	v_readlane_b32 s0, v240, 24
	v_readlane_b32 s1, v240, 25
	s_bitcmp1_b32 s0, 0
	s_cselect_b64 s[0:1], -1, 0
	s_xor_b64 s[88:89], s[0:1], -1
	v_readlane_b32 s2, v240, 12
	s_mov_b32 s5, s92
	v_and_b32_e32 v212, 31, v135
	v_lshrrev_b32_e32 v214, 5, v135
	v_lshlrev_b32_e32 v213, 4, v214
	v_lshlrev_b32_e32 v214, 5, v214
	v_sub_u32_e32 v215, 31, v212
	v_lshl_add_u32 v212, v212, 8, v213
	v_lshl_add_u32 v213, v215, 8, v213
	s_mov_b32 s98, s2
	s_mul_hi_u32 s99, s98, 0xf0f0f0f1
	s_lshr_b32 s100, s99, 7
	s_mul_i32 s101, s100, 0x88
	s_sub_i32 s98, s98, s101
	s_lshr_b32 s99, s99, 9
	s_and_b32 s100, s100, 3
	s_lshl_b32 s101, s98, 5
	s_cmp_gt_u32 s98, 7
	s_cbranch_scc1 .Lpf_lat_a
	s_lshl_b32 s99, s99, 8
	s_add_i32 s101, s101, 0x8000
	s_branch .Lpf_join_a
.Lpf_lat_a:
	s_lshl_b32 s99, s99, 12
	s_add_i32 s101, s101, 0xffffff00
.Lpf_join_a:
	s_add_i32 s101, s101, s99
	s_mul_i32 s32, s100, 0x880000
	s_lshl_b32 s11, s101, 8
	s_add_u32 s32, s32, s11
	s_lshl_b32 s22, s100, 9
	s_add_u32 s18, s82, s32
	s_addc_u32 s19, s83, 0
	s_add_u32 s20, s18, 0x2200000
	s_addc_u32 s21, s19, 0
	s_add_u32 s98, s18, 0x4400000
	s_addc_u32 s99, s19, 0
	s_add_u32 s100, s18, 0x6600000
	s_addc_u32 s101, s19, 0
	global_load_dwordx4 v[188:191], v212, s[18:19]
	global_load_dwordx4 v[192:195], v212, s[100:101]
	global_load_dwordx4 v[196:199], v212, s[98:99]
	global_load_dwordx4 v[200:203], v213, s[20:21]
	global_load_dwordx4 v[204:207], v213, s[100:101]
	global_load_dwordx4 v[208:211], v213, s[98:99]
	s_add_u32 s20, s85, s22
	v_readlane_b32 s21, v243, 43
	s_nop 1
	s_addc_u32 s21, s21, 0
	s_nop 4
	global_load_dwordx4 v[156:159], v214, s[20:21]
	global_load_dwordx4 v[160:163], v214, s[20:21] offset:16
	global_load_dwordx4 v[168:171], v214, s[20:21] offset:2048
	global_load_dwordx4 v[172:175], v214, s[20:21] offset:2064
	s_waitcnt vmcnt(0)
	s_branch .LBB0_243

; #define LAS __attribute__((address_space(3)))
; __device__ __forceinline__ size_t PIX(int row, int col) { return (size_t)(col >> 7) * PSLOT + (size_t)row * 128 + (col & 127); }
; __device__ __forceinline__ int opaque_tid() { int t = threadIdx.x; asm volatile("" : "+v"(t)); return t; }
; __device__ void prep_item(const Params& p, int l, int item, LAS unsigned char* lds) {
;     const int tid = opaque_tid(), w = tid >> 6, lane = tid & 63;
;     const int tau = lane & 31, kh = lane >> 5, k0 = 16 * w + 8 * kh, l15 = lane & 15, q4 = lane >> 4;
;     const int ci = item % NCH, bh = item / NCH, h = bh & 3, b = bh >> 2;
;     const int R0 = ci < 8 ? NLAT + b * 256 + 32 * ci : b * 4096 + 32 * (ci - 8);
;     bf16_t* P = (bf16_t*)(p.ws + WS_BIG);
;     const bool first = (l == 0);
;     const bool want_out = first || ci >= 8;
;     for (int dd = 0; dd < 2; ++dd) { LAS unsigned* az = (LAS unsigned*)(lds + dd * P1_DIRSZ + P1_AW) + w * (32 * KT_ST / 2); for (int i = lane; i < 32 * KT_ST / 2; i += 64) az[i] = 0u; }
;     u32x4 rf0, rq0, rv0, rf1, rq1, rv1;
;     { const int r_ = R0 + tau; rf0 = *(const u32x4*)(P + PIX(r_, h * 128 + k0)); rq0 = *(const u32x4*)(P + PIX(r_, 1536 + h * 128 + k0)); rv0 = *(const u32x4*)(P + PIX(r_, 1024 + h * 128 + k0)); }
;     { const int r_ = R0 + 31 - tau; rf1 = *(const u32x4*)(P + PIX(r_, 512 + h * 128 + k0)); rq1 = *(const u32x4*)(P + PIX(r_, 1536 + h * 128 + k0)); rv1 = *(const u32x4*)(P + PIX(r_, 1024 + h * 128 + k0)); }
;     asm volatile("s_waitcnt vmcnt(0)" ::: "memory");
;     __syncthreads();
.LBB0_247:
	v_ashrrev_i32_e32 v1, 6, v54
	s_and_b32 s74, s6, 3
	v_lshlrev_b32_e32 v30, 4, v1
	s_lshl_b32 s6, s74, 7
	v_and_b32_e32 v31, 31, v54
	v_lshrrev_b32_e32 v0, 2, v54
	v_add_u32_e32 v3, s6, v30
	v_and_b32_e32 v0, 8, v0
	v_add_u32_e32 v2, s70, v31
	v_ashrrev_i32_e32 v4, 7, v3
	v_mov_b32_e32 v3, v8
	s_movk_i32 s0, 0x78
	v_mov_b64_e32 v[10:11], s[82:83]
	v_bitop3_b32 v6, v30, s0, v0 bitop3:0xc8
	v_mad_i64_i32 v[4:5], s[0:1], v4, s87, v[10:11]
	v_lshlrev_b64 v[36:37], 8, v[2:3]
	s_or_b32 s7, s6, 0x600
	v_lshl_add_u64 v[2:3], v[4:5], 0, v[36:37]
	v_add_u32_e32 v4, s7, v30
	v_ashrrev_i32_e32 v4, 7, v4
	v_lshlrev_b32_e32 v12, 1, v6
	v_mov_b32_e32 v13, v8
	v_mad_i64_i32 v[14:15], s[0:1], v4, s87, v[10:11]
	v_lshl_add_u64 v[2:3], v[2:3], 0, v[12:13]
	v_lshl_add_u64 v[4:5], v[14:15], 0, v[36:37]
	v_lshl_add_u64 v[16:17], v[4:5], 0, v[12:13]
	s_or_b32 s72, s6, 0x400
	s_or_b32 s71, s6, 0x200
	v_add_u32_e32 v2, s72, v30
	v_bitop3_b32 v56, v54, 31, v54 bitop3:0xc
	v_add_u32_e32 v9, s71, v30
	v_ashrrev_i32_e32 v2, 7, v2
	v_add_u32_e32 v18, s70, v56
	v_ashrrev_i32_e32 v9, 7, v9
	v_mov_b32_e32 v19, v8
	v_mad_i64_i32 v[2:3], s[0:1], v2, s87, v[10:11]
	v_mad_i64_i32 v[10:11], s[0:1], v9, s87, v[10:11]
	v_lshlrev_b64 v[32:33], 8, v[18:19]
	v_lshl_add_u64 v[16:17], v[2:3], 0, v[36:37]
	v_lshl_add_u64 v[10:11], v[10:11], 0, v[32:33]
	v_lshl_add_u64 v[16:17], v[16:17], 0, v[12:13]
	v_lshl_add_u64 v[10:11], v[10:11], 0, v[12:13]
	v_lshl_add_u64 v[10:11], v[14:15], 0, v[32:33]
	v_lshl_add_u64 v[10:11], v[10:11], 0, v[12:13]
	v_lshl_add_u64 v[2:3], v[2:3], 0, v[32:33]
	v_lshl_add_u64 v[2:3], v[2:3], 0, v[12:13]
	s_nop 0
	s_movk_i32 s0, 0xa00
	v_and_b32_e32 v57, 63, v54
	v_mul_lo_u32 v1, v1, s0
	v_readlane_b32 s1, v240, 18
	v_cndmask_b32_e64 v2, 0, 1, s[88:89]
	v_lshlrev_b32_e32 v3, 2, v57
	v_add_u32_e32 v55, 16, v1
	v_add_u32_e32 v9, s1, v1
	v_cmp_ne_u32_e64 s[40:41], 1, v2
	v_add_u32_e32 v1, v55, v3
	v_add_u32_e32 v2, v9, v3
	ds_write2st64_b32 v1, v8, v8 offset0:148 offset1:149
	ds_write2st64_b32 v1, v8, v8 offset0:150 offset1:151
	ds_write2st64_b32 v1, v8, v8 offset0:152 offset1:153
	ds_write2st64_b32 v1, v8, v8 offset0:154 offset1:155
	ds_write2st64_b32 v1, v8, v8 offset0:156 offset1:157
	ds_write2st64_b32 v2, v8, v8 offset1:1
	ds_write2st64_b32 v2, v8, v8 offset0:2 offset1:3
	ds_write2st64_b32 v2, v8, v8 offset0:4 offset1:5
	ds_write2st64_b32 v2, v8, v8 offset0:6 offset1:7
	ds_write2st64_b32 v2, v8, v8 offset0:8 offset1:9
	s_lshl_b32 s0, s74, 9
	s_waitcnt vmcnt(3)
	v_mov_b64_e32 v[4:5], v[188:189]
	v_mov_b64_e32 v[6:7], v[190:191]
	v_mov_b64_e32 v[26:27], v[192:193]
	v_mov_b64_e32 v[28:29], v[194:195]
	v_mov_b64_e32 v[22:23], v[196:197]
	v_mov_b64_e32 v[24:25], v[198:199]
	v_mov_b64_e32 v[18:19], v[200:201]
	v_mov_b64_e32 v[20:21], v[202:203]
	v_mov_b64_e32 v[14:15], v[204:205]
	v_mov_b64_e32 v[16:17], v[206:207]
	v_mov_b64_e32 v[10:11], v[208:209]
	v_mov_b64_e32 v[12:13], v[210:211]
	s_sub_i32 s98, s2, s46
	s_cmp_lt_i32 s98, 0
	s_cselect_b32 s98, s2, s98
	s_mul_hi_u32 s99, s98, 0xf0f0f0f1
	s_lshr_b32 s100, s99, 7
	s_mul_i32 s101, s100, 0x88
	s_sub_i32 s98, s98, s101
	s_lshr_b32 s99, s99, 9
	s_and_b32 s100, s100, 3
	s_lshl_b32 s101, s98, 5
	s_cmp_gt_u32 s98, 7
	s_cbranch_scc1 .Lpf_lat_b
	s_lshl_b32 s99, s99, 8
	s_add_i32 s101, s101, 0x8000
	s_branch .Lpf_join_b

; #define LAS __attribute__((address_space(3)))
; __device__ __forceinline__ size_t PIX(int row, int col) { return (size_t)(col >> 7) * PSLOT + (size_t)row * 128 + (col & 127); }
; __device__ __forceinline__ float bf_lo(unsigned u) { return __uint_as_float(u << 16); }
; __device__ __forceinline__ float bf_hi(unsigned u) { return __uint_as_float(u & 0xffff0000u); }
; __device__ __forceinline__ float fast_rcp(float x) { return __builtin_amdgcn_rcpf(x); }
; __device__ void prep_item(const Params& p, int l, int item, LAS unsigned char* lds) {
;     ...
;     { const int r_ = R0 + tau; rf0 = *(const u32x4*)(P + PIX(r_, h * 128 + k0)); rq0 = *(const u32x4*)(P + PIX(r_, 1536 + h * 128 + k0)); rv0 = *(const u32x4*)(P + PIX(r_, 1024 + h * 128 + k0)); }
;     { const int r_ = R0 + 31 - tau; rf1 = *(const u32x4*)(P + PIX(r_, 512 + h * 128 + k0)); rq1 = *(const u32x4*)(P + PIX(r_, 1536 + h * 128 + k0)); rv1 = *(const u32x4*)(P + PIX(r_, 1024 + h * 128 + k0)); }
;     asm volatile("s_waitcnt vmcnt(0)" ::: "memory");
;     __syncthreads();
;     auto valu_part = [&](const int dir, const u32x4& f, const u32x4& q, const u32x4& v) {
;         LAS unsigned char* db = lds + dir * P1_DIRSZ;
;         LAS bf16_t* Qs = (LAS bf16_t*)(db + P1_QS); LAS bf16_t* Kh = (LAS bf16_t*)(db + P1_KH);
;         LAS bf16_t* Vt = (LAS bf16_t*)(db + P1_VT); LAS bf16_t* Kt = (LAS bf16_t*)(db + P1_KT);
;         LAS bf16_t* Aw = (LAS bf16_t*)(db + P1_AW) + w * 32 * KT_ST;
;         const int tokl = dir ? 31 - tau : tau;
;         const float* lbp = (const float*)(p.ws + WS_LB) + dir * 512 + h * 128 + k0;
;         float E[8], kk[8];
; #pragma unroll
;         for (int j = 0; j < 8; ++j) {
;             const unsigned fw = f[j >> 1]; const float x = (j & 1) ? bf_hi(fw) : bf_lo(fw);
;             const float e = __expf(-fabsf(x)), r = fast_rcp(1.0f + e);
;             const float sp = x >= 0.f ? r : e * r, sn = x >= 0.f ? e * r : r;
;             if (first) { E[j] = sp; kk[j] = sn; }
;             else { const float lb = lbp[j]; const float gate = lb + (1.0f - lb) * sp; E[j] = gate; kk[j] = 1.0f - gate; }
.Lpf_join_b:
	s_add_i32 s101, s101, s99
	s_mul_i32 s32, s100, 0x880000
	s_lshl_b32 s11, s101, 8
	s_add_u32 s32, s32, s11
	s_lshl_b32 s22, s100, 9
	s_add_u32 s18, s82, s32
	s_addc_u32 s19, s83, 0
	s_add_u32 s20, s18, 0x2200000
	s_addc_u32 s21, s19, 0
	s_add_u32 s98, s18, 0x4400000
	s_addc_u32 s99, s19, 0
	s_add_u32 s100, s18, 0x6600000
	s_addc_u32 s101, s19, 0
	global_load_dwordx4 v[188:191], v212, s[18:19]
	global_load_dwordx4 v[192:195], v212, s[100:101]
	global_load_dwordx4 v[196:199], v212, s[98:99]
	global_load_dwordx4 v[200:203], v213, s[20:21]
	global_load_dwordx4 v[204:207], v213, s[100:101]
	global_load_dwordx4 v[208:211], v213, s[98:99]
	s_add_u32 s38, s85, s0
	v_readlane_b32 s0, v243, 43
	s_addc_u32 s39, s0, 0
	s_andn2_b64 vcc, exec, s[88:89]
	s_mov_b64 s[42:43], -1
	s_waitcnt lgkmcnt(0)
	s_barrier
	v_lshlrev_b32_e32 v2, 16, v4
	v_mul_f32_e64 v1, |v2|, s69
	v_exp_f32_e32 v3, v1
	v_cmp_le_f32_e64 s[0:1], 0, v2
	v_add_f32_e32 v1, 1.0, v3
	v_rcp_f32_e32 v1, v1
	s_nop 0
	v_mul_f32_e32 v2, v3, v1
	s_cbranch_vccnz .LBB0_249
	v_cndmask_b32_e64 v38, v1, v2, s[0:1]
	s_mov_b64 s[42:43], 0
.LBB0_249:
	v_or_b32_e32 v34, v30, v0
	v_ashrrev_i32_e32 v35, 31, v34
	v_lshl_add_u64 v[42:43], v[34:35], 2, s[38:39]
	s_andn2_b64 vcc, exec, s[42:43]
	v_cndmask_b32_e64 v0, v2, v1, s[0:1]
	s_cbranch_vccnz .LBB0_251
	v_mov_b32_e32 v1, v156
	v_sub_f32_e32 v2, 1.0, v1
	v_fmac_f32_e32 v1, v0, v2
	v_sub_f32_e32 v38, 1.0, v1
	v_mov_b32_e32 v0, v1

; __device__ __forceinline__ float bf_lo(unsigned u) { return __uint_as_float(u << 16); }
; __device__ __forceinline__ float bf_hi(unsigned u) { return __uint_as_float(u & 0xffff0000u); }
; __device__ __forceinline__ float fast_rcp(float x) { return __builtin_amdgcn_rcpf(x); }
; __device__ void prep_item(const Params& p, int l, int item, LAS unsigned char* lds) {
;     ...
;         for (int j = 0; j < 8; ++j) {
;             const unsigned fw = f[j >> 1]; const float x = (j & 1) ? bf_hi(fw) : bf_lo(fw);
;             const float e = __expf(-fabsf(x)), r = fast_rcp(1.0f + e);
;             const float sp = x >= 0.f ? r : e * r, sn = x >= 0.f ? e * r : r;
;             if (first) { E[j] = sp; kk[j] = sn; }
;             else { const float lb = lbp[j]; const float gate = lb + (1.0f - lb) * sp; E[j] = gate; kk[j] = 1.0f - gate; }
.LBB0_253:
	s_andn2_b64 vcc, exec, s[38:39]
	s_cbranch_vccnz .LBB0_255
	v_mov_b32_e32 v1, v157
	v_sub_f32_e32 v3, 1.0, v1
	v_fmac_f32_e32 v1, v2, v3
	v_sub_f32_e32 v39, 1.0, v1

; __device__ __forceinline__ float bf_lo(unsigned u) { return __uint_as_float(u << 16); }
; __device__ __forceinline__ float bf_hi(unsigned u) { return __uint_as_float(u & 0xffff0000u); }
; __device__ __forceinline__ float fast_rcp(float x) { return __builtin_amdgcn_rcpf(x); }
; __device__ void prep_item(const Params& p, int l, int item, LAS unsigned char* lds) {
;     ...
;         for (int j = 0; j < 8; ++j) {
;             const unsigned fw = f[j >> 1]; const float x = (j & 1) ? bf_hi(fw) : bf_lo(fw);
;             const float e = __expf(-fabsf(x)), r = fast_rcp(1.0f + e);
;             const float sp = x >= 0.f ? r : e * r, sn = x >= 0.f ? e * r : r;
;             if (first) { E[j] = sp; kk[j] = sn; }
;             else { const float lb = lbp[j]; const float gate = lb + (1.0f - lb) * sp; E[j] = gate; kk[j] = 1.0f - gate; }
.LBB0_257:
	s_andn2_b64 vcc, exec, s[38:39]
	s_cbranch_vccnz .LBB0_259
	v_mov_b32_e32 v2, v158
	v_sub_f32_e32 v4, 1.0, v2
	v_fmac_f32_e32 v2, v3, v4
	v_sub_f32_e32 v40, 1.0, v2

; __device__ __forceinline__ float bf_lo(unsigned u) { return __uint_as_float(u << 16); }
; __device__ __forceinline__ float bf_hi(unsigned u) { return __uint_as_float(u & 0xffff0000u); }
; __device__ __forceinline__ float fast_rcp(float x) { return __builtin_amdgcn_rcpf(x); }
; __device__ void prep_item(const Params& p, int l, int item, LAS unsigned char* lds) {
;     ...
;         for (int j = 0; j < 8; ++j) {
;             const unsigned fw = f[j >> 1]; const float x = (j & 1) ? bf_hi(fw) : bf_lo(fw);
;             const float e = __expf(-fabsf(x)), r = fast_rcp(1.0f + e);
;             const float sp = x >= 0.f ? r : e * r, sn = x >= 0.f ? e * r : r;
;             if (first) { E[j] = sp; kk[j] = sn; }
;             else { const float lb = lbp[j]; const float gate = lb + (1.0f - lb) * sp; E[j] = gate; kk[j] = 1.0f - gate; }
.LBB0_261:
	s_andn2_b64 vcc, exec, s[38:39]
	s_cbranch_vccnz .LBB0_263
	v_mov_b32_e32 v3, v159
	v_sub_f32_e32 v5, 1.0, v3
	v_fmac_f32_e32 v3, v4, v5
	v_sub_f32_e32 v41, 1.0, v3

; __device__ __forceinline__ float bf_lo(unsigned u) { return __uint_as_float(u << 16); }
; __device__ __forceinline__ float bf_hi(unsigned u) { return __uint_as_float(u & 0xffff0000u); }
; __device__ __forceinline__ float fast_rcp(float x) { return __builtin_amdgcn_rcpf(x); }
; __device__ void prep_item(const Params& p, int l, int item, LAS unsigned char* lds) {
;     ...
;         for (int j = 0; j < 8; ++j) {
;             const unsigned fw = f[j >> 1]; const float x = (j & 1) ? bf_hi(fw) : bf_lo(fw);
;             const float e = __expf(-fabsf(x)), r = fast_rcp(1.0f + e);
;             const float sp = x >= 0.f ? r : e * r, sn = x >= 0.f ? e * r : r;
;             if (first) { E[j] = sp; kk[j] = sn; }
;             else { const float lb = lbp[j]; const float gate = lb + (1.0f - lb) * sp; E[j] = gate; kk[j] = 1.0f - gate; }
.LBB0_265:
	s_andn2_b64 vcc, exec, s[38:39]
	s_cbranch_vccnz .LBB0_267
	v_mov_b32_e32 v4, v160
	v_sub_f32_e32 v44, 1.0, v4
	v_fmac_f32_e32 v4, v5, v44
	v_sub_f32_e32 v44, 1.0, v4

; __device__ __forceinline__ float bf_lo(unsigned u) { return __uint_as_float(u << 16); }
; __device__ __forceinline__ float bf_hi(unsigned u) { return __uint_as_float(u & 0xffff0000u); }
; __device__ __forceinline__ float fast_rcp(float x) { return __builtin_amdgcn_rcpf(x); }
; __device__ void prep_item(const Params& p, int l, int item, LAS unsigned char* lds) {
;     ...
;         for (int j = 0; j < 8; ++j) {
;             const unsigned fw = f[j >> 1]; const float x = (j & 1) ? bf_hi(fw) : bf_lo(fw);
;             const float e = __expf(-fabsf(x)), r = fast_rcp(1.0f + e);
;             const float sp = x >= 0.f ? r : e * r, sn = x >= 0.f ? e * r : r;
;             if (first) { E[j] = sp; kk[j] = sn; }
;             else { const float lb = lbp[j]; const float gate = lb + (1.0f - lb) * sp; E[j] = gate; kk[j] = 1.0f - gate; }
.LBB0_269:
	s_andn2_b64 vcc, exec, s[38:39]
	s_cbranch_vccnz .LBB0_271
	v_mov_b32_e32 v5, v161
	v_sub_f32_e32 v45, 1.0, v5
	v_fmac_f32_e32 v5, v6, v45
	v_sub_f32_e32 v45, 1.0, v5

; __device__ __forceinline__ float bf_lo(unsigned u) { return __uint_as_float(u << 16); }
; __device__ __forceinline__ float bf_hi(unsigned u) { return __uint_as_float(u & 0xffff0000u); }
; __device__ __forceinline__ float fast_rcp(float x) { return __builtin_amdgcn_rcpf(x); }
; __device__ void prep_item(const Params& p, int l, int item, LAS unsigned char* lds) {
;     ...
;         for (int j = 0; j < 8; ++j) {
;             const unsigned fw = f[j >> 1]; const float x = (j & 1) ? bf_hi(fw) : bf_lo(fw);
;             const float e = __expf(-fabsf(x)), r = fast_rcp(1.0f + e);
;             const float sp = x >= 0.f ? r : e * r, sn = x >= 0.f ? e * r : r;
;             if (first) { E[j] = sp; kk[j] = sn; }
;             else { const float lb = lbp[j]; const float gate = lb + (1.0f - lb) * sp; E[j] = gate; kk[j] = 1.0f - gate; }
.LBB0_273:
	s_andn2_b64 vcc, exec, s[38:39]
	s_cbranch_vccnz .LBB0_275
	v_mov_b32_e32 v6, v162
	v_sub_f32_e32 v46, 1.0, v6
	v_fmac_f32_e32 v6, v47, v46
	v_sub_f32_e32 v46, 1.0, v6

; __device__ __forceinline__ float bf_lo(unsigned u) { return __uint_as_float(u << 16); }
; __device__ __forceinline__ float bf_hi(unsigned u) { return __uint_as_float(u & 0xffff0000u); }
; __device__ __forceinline__ float fast_rcp(float x) { return __builtin_amdgcn_rcpf(x); }
; __device__ void prep_item(const Params& p, int l, int item, LAS unsigned char* lds) {
;     ...
;         for (int j = 0; j < 8; ++j) {
;             const unsigned fw = f[j >> 1]; const float x = (j & 1) ? bf_hi(fw) : bf_lo(fw);
;             const float e = __expf(-fabsf(x)), r = fast_rcp(1.0f + e);
;             const float sp = x >= 0.f ? r : e * r, sn = x >= 0.f ? e * r : r;
;             if (first) { E[j] = sp; kk[j] = sn; }
;             else { const float lb = lbp[j]; const float gate = lb + (1.0f - lb) * sp; E[j] = gate; kk[j] = 1.0f - gate; }
.LBB0_277:
	s_andn2_b64 vcc, exec, s[38:39]
	s_cbranch_vccnz .LBB0_279
	v_mov_b32_e32 v7, v163
	v_sub_f32_e32 v42, 1.0, v7
	v_fmac_f32_e32 v7, v48, v42
	v_sub_f32_e32 v47, 1.0, v7

; __device__ void prep_item(const Params& p, int l, int item, LAS unsigned char* lds) {
;     ...
;         for (int j = 0; j < 8; ++j) {
;             const unsigned fw = f[j >> 1]; const float x = (j & 1) ? bf_hi(fw) : bf_lo(fw);
;             const float e = __expf(-fabsf(x)), r = fast_rcp(1.0f + e);
;             const float sp = x >= 0.f ? r : e * r, sn = x >= 0.f ? e * r : r;
;     ...
;         float qt[8], kh_[8], kt_[8], Tj[8];
;         cumprod32x8(E);
; #pragma unroll
;         for (int j = 0; j < 8; ++j) {
;             const float Ej = fmaxf(E[j], 1e-35f);
;             const float T0 = __builtin_bit_cast(float, __builtin_amdgcn_readlane(__builtin_bit_cast(int, Ej), 31)), T1 = __builtin_bit_cast(float, __builtin_amdgcn_readlane(__builtin_bit_cast(int, Ej), 63));
;             const float T = kh ? T1 : T0;
;             const unsigned qw = q[j >> 1]; const float qx = (j & 1) ? bf_hi(qw) : bf_lo(qw);
;             qt[j] = silu_f(qx) * 0.08838834764831845f * Ej;
;             kh_[j] = kk[j] * fast_rcp(Ej); kt_[j] = kh_[j] * T;
;             Tj[j] = T;
;         }
;         if (tau == 31) { float* dp = (float*)(p.ws + WS_DS) + ((size_t)((b * 4 + h) * 2 + dir) * NCH + ci) * 128 + k0;
;             *(f32x4*)dp = (f32x4){Tj[0], Tj[1], Tj[2], Tj[3]}; *(f32x4*)(dp + 4) = (f32x4){Tj[4], Tj[5], Tj[6], Tj[7]}; }
;         u32x4 wq, wk; wq.x = pk_bf16(qt[0], qt[1]); wq.y = pk_bf16(qt[2], qt[3]); wq.z = pk_bf16(qt[4], qt[5]); wq.w = pk_bf16(qt[6], qt[7]);
;         wk.x = pk_bf16(kh_[0], kh_[1]); wk.y = pk_bf16(kh_[2], kh_[3]); wk.z = pk_bf16(kh_[4], kh_[5]); wk.w = pk_bf16(kh_[6], kh_[7]);
;         *(LAS u32x4*)(Qs + tau * QS_ST + k0) = wq; *(LAS u32x4*)(Kh + tau * QS_ST + k0) = wk;
;         {
;           bf16_t* qd = (dir == 0) ? P + PIX(R0 + tokl, 1536 + h * 128) : (bf16_t*)(p.ws + WS_QB) + (size_t)h * PSLOT + (size_t)(R0 + tokl) * 128;
;           const int a32 = k0 & ~31, kkA = k0 & 31, kkB = kkA + 4;
;           u32x2 pa, pb; pa.x = wq.x; pa.y = wq.y; pb.x = wq.z; pb.y = wq.w;
;           *(u32x2*)(qd + a32 + 8 * ((kkA & 15) >> 2) + 4 * (kkA >> 4)) = pa;
;           *(u32x2*)(qd + a32 + 8 * ((kkB & 15) >> 2) + 4 * (kkB >> 4)) = pb; }
; #pragma unroll
;         for (int j = 0; j < 8; ++j) { Kt[(k0 + j) * KT_ST + tokl] = to_bf1(kt_[j]); const unsigned vw = v[j >> 1]; Vt[(k0 + j) * KT_ST + tau] = (bf16_t)((j & 1) ? (vw >> 16) : (vw & 0xffffu)); }
.LBB0_281:
	s_or_b64 exec, exec, s[0:1]
	v_lshlrev_b32_e32 v58, 16, v26
	v_and_b32_e32 v59, 0xffff0000, v26
	v_mul_f32_e32 v26, 0xbfb8aa3b, v58
	v_exp_f32_e32 v26, v26
	v_mul_f32_e32 v60, 0xbfb8aa3b, v59
	v_exp_f32_e32 v61, v60
	s_movk_i32 s0, 0x110
	v_add_f32_e32 v26, 1.0, v26
	v_rcp_f32_e32 v60, v26
	v_add_f32_e32 v26, 1.0, v61
	v_rcp_f32_e32 v61, v26
	v_rcp_f32_e32 v26, v52
	v_pk_mul_f32 v[58:59], v[60:61], v[58:59]
	v_lshlrev_b32_e32 v60, 16, v27
	v_and_b32_e32 v61, 0xffff0000, v27
	v_mul_f32_e32 v27, 0xbfb8aa3b, v60
	v_exp_f32_e32 v62, v27
	v_mul_f32_e32 v27, 0xbfb8aa3b, v61
	v_exp_f32_e32 v63, v27
	v_rcp_f32_e32 v27, v53
	v_add_f32_e32 v62, 1.0, v62
	v_rcp_f32_e32 v62, v62
	v_add_f32_e32 v63, 1.0, v63
	v_rcp_f32_e32 v63, v63
	v_pk_mul_f32 v[58:59], v[58:59], s[86:87] op_sel_hi:[1,0]
	s_nop 0
	v_pk_mul_f32 v[52:53], v[58:59], v[52:53]
	v_pk_mul_f32 v[58:59], v[38:39], v[26:27]
	v_pk_mul_f32 v[38:39], v[62:63], v[60:61]
	v_lshlrev_b32_e32 v60, 16, v28
	v_and_b32_e32 v61, 0xffff0000, v28
	v_mul_f32_e32 v27, 0xbfb8aa3b, v60
	v_exp_f32_e32 v28, v27
	v_mul_f32_e32 v27, 0xbfb8aa3b, v61
	v_exp_f32_e32 v63, v27
	v_rcp_f32_e32 v26, v50
	v_add_f32_e32 v28, 1.0, v28
	v_rcp_f32_e32 v62, v28
	v_add_f32_e32 v28, 1.0, v63
	v_rcp_f32_e32 v63, v28
	v_rcp_f32_e32 v27, v51
	v_pk_mul_f32 v[38:39], v[38:39], s[86:87] op_sel_hi:[1,0]
	v_lshlrev_b32_e32 v28, 16, v29
	v_pk_mul_f32 v[50:51], v[38:39], v[50:51]
	v_pk_mul_f32 v[38:39], v[62:63], v[60:61]
	v_pk_mul_f32 v[64:65], v[40:41], v[26:27]
	v_pk_mul_f32 v[38:39], v[38:39], s[86:87] op_sel_hi:[1,0]
	v_and_b32_e32 v29, 0xffff0000, v29
	v_mul_f32_e32 v27, 0xbfb8aa3b, v28
	v_pk_mul_f32 v[40:41], v[38:39], v[48:49]
	v_exp_f32_e32 v38, v27
	v_mul_f32_e32 v27, 0xbfb8aa3b, v29
	v_exp_f32_e32 v39, v27
	v_rcp_f32_e32 v26, v48
	v_rcp_f32_e32 v27, v49
	v_add_f32_e32 v38, 1.0, v38
	v_add_f32_e32 v39, 1.0, v39
	v_rcp_f32_e32 v38, v38
	v_rcp_f32_e32 v39, v39
	v_pk_mul_f32 v[44:45], v[44:45], v[26:27]
	v_rcp_f32_e32 v26, v42
	v_rcp_f32_e32 v27, v43
	v_pk_mul_f32 v[28:29], v[38:39], v[28:29]
	v_mad_u32_u24 v49, v31, s0, 16
	v_pk_mul_f32 v[28:29], v[28:29], s[86:87] op_sel_hi:[1,0]
	s_lshr_b32 s0, s7, 7
	v_pk_mul_f32 v[28:29], v[28:29], v[42:43]
	v_pk_mul_f32 v[42:43], v[46:47], v[26:27]
	v_lshlrev_b32_e32 v46, 1, v34
	s_mul_i32 s0, s0, 0x880000
	v_cvt_pk_bf16_f32 v38, v52, v53
	v_cvt_pk_bf16_f32 v39, v50, v51
	v_cvt_pk_bf16_f32 v40, v40, v41
	v_cvt_pk_bf16_f32 v41, v28, v29
	v_cvt_pk_bf16_f32 v26, v58, v59
	v_add_u32_e32 v47, v49, v46
	s_add_u32 s0, s82, s0
	v_cvt_pk_bf16_f32 v27, v64, v65
	v_cvt_pk_bf16_f32 v28, v44, v45
	v_cvt_pk_bf16_f32 v29, v42, v43
	ds_write_b128 v47, v[38:41]
	ds_write_b128 v47, v[26:29] offset:8704
	s_addc_u32 s1, s83, 0
	v_and_b32_e32 v26, 0xffffffe0, v30
	v_lshl_add_u64 v[28:29], s[0:1], 0, v[36:37]
	v_ashrrev_i32_e32 v27, 31, v26
	v_mul_f32_e32 v7, v43, v7
	v_mul_f32_e32 v6, v42, v6
	v_mul_f32_e32 v42, v59, v1
	v_mul_f32_e32 v43, v58, v0
	v_lshl_add_u64 v[0:1], v[26:27], 1, v[28:29]
	v_and_b32_e32 v28, 16, v46
	v_lshlrev_b32_e32 v28, 1, v28
	v_mov_b32_e32 v29, v8
	v_lshl_add_u64 v[0:1], v[0:1], 0, v[28:29]
	v_lshrrev_b32_e32 v29, 2, v30
	v_and_b32_e32 v29, 4, v29
	v_lshlrev_b32_e32 v36, 1, v29
	v_mov_b32_e32 v37, v8
	v_lshl_add_u64 v[0:1], v[0:1], 0, v[36:37]
	global_store_dwordx2 v[0:1], v[38:39], off
	global_store_dwordx2 v[0:1], v[40:41], off offset:16
	v_cvt_pk_bf16_f32 v1, v43, s0
	s_movk_i32 s0, 0x50
	v_mul_i32_i24_e32 v0, 0xfffffef2, v31
	v_mul_lo_u32 v48, v34, s0
	v_add3_u32 v0, v49, v0, v48
	v_mul_f32_e32 v2, v64, v2
	ds_write_b16 v0, v1 offset:27648
	ds_write_b16 v0, v22 offset:17408
	v_cvt_pk_bf16_f32 v1, v42, s0
	v_mul_f32_e32 v3, v65, v3
	ds_write_b16 v0, v1 offset:27728
	ds_write_b16_d16_hi v0, v22 offset:17488
	v_cvt_pk_bf16_f32 v1, v2, s0
	v_lshlrev_b32_e32 v2, 16, v18
	v_mul_f32_e32 v4, v44, v4
	ds_write_b16 v0, v1 offset:27808
	ds_write_b16 v0, v23 offset:17568
	v_cvt_pk_bf16_f32 v1, v3, s0
	v_mul_f32_e64 v3, |v2|, s69
	v_mul_f32_e32 v5, v45, v5
	ds_write_b16 v0, v1 offset:27888
	ds_write_b16_d16_hi v0, v23 offset:17648
	v_cvt_pk_bf16_f32 v1, v4, s0
	v_exp_f32_e32 v3, v3
	ds_write_b16 v0, v1 offset:27968
	ds_write_b16 v0, v24 offset:17728
	v_cvt_pk_bf16_f32 v1, v5, s0
	ds_write_b16 v0, v1 offset:28048
	ds_write_b16_d16_hi v0, v24 offset:17808
	v_cvt_pk_bf16_f32 v1, v6, s0
	ds_write_b16 v0, v1 offset:28128
	ds_write_b16 v0, v25 offset:17888
	v_cvt_pk_bf16_f32 v1, v7, s0
	ds_write_b16 v0, v1 offset:28208
	ds_write_b16_d16_hi v0, v25 offset:17968
	v_add_f32_e32 v0, 1.0, v3
	v_rcp_f32_e32 v0, v0
	s_lshl_b32 s0, s6, 2
	v_readlane_b32 s1, v243, 44
	s_add_u32 s66, s1, s0
	v_readlane_b32 s0, v243, 45
	s_addc_u32 s67, s0, 0
	v_cmp_le_f32_e64 s[0:1], 0, v2
	v_mul_f32_e32 v1, v3, v0
	s_and_b64 vcc, exec, s[40:41]
	s_mov_b64 s[40:41], -1
	s_cbranch_vccnz .LBB0_283
	v_cndmask_b32_e64 v22, v0, v1, s[0:1]
	s_mov_b64 s[40:41], 0
.LBB0_283:
	v_lshl_add_u64 v[38:39], v[34:35], 2, s[66:67]
	s_andn2_b64 vcc, exec, s[40:41]
	v_cndmask_b32_e64 v0, v1, v0, s[0:1]
	s_cbranch_vccnz .LBB0_285
	v_mov_b32_e32 v1, v168
	v_sub_f32_e32 v2, 1.0, v1
	v_fmac_f32_e32 v1, v0, v2
	v_sub_f32_e32 v22, 1.0, v1
	v_mov_b32_e32 v0, v1

; __device__ __forceinline__ float bf_lo(unsigned u) { return __uint_as_float(u << 16); }
; __device__ __forceinline__ float bf_hi(unsigned u) { return __uint_as_float(u & 0xffff0000u); }
; __device__ __forceinline__ float fast_rcp(float x) { return __builtin_amdgcn_rcpf(x); }
; __device__ void prep_item(const Params& p, int l, int item, LAS unsigned char* lds) {
;     ...
;         for (int j = 0; j < 8; ++j) {
;             const unsigned fw = f[j >> 1]; const float x = (j & 1) ? bf_hi(fw) : bf_lo(fw);
;             const float e = __expf(-fabsf(x)), r = fast_rcp(1.0f + e);
;             const float sp = x >= 0.f ? r : e * r, sn = x >= 0.f ? e * r : r;
;             if (first) { E[j] = sp; kk[j] = sn; }
;             else { const float lb = lbp[j]; const float gate = lb + (1.0f - lb) * sp; E[j] = gate; kk[j] = 1.0f - gate; }
.LBB0_287:
	s_andn2_b64 vcc, exec, s[40:41]
	s_cbranch_vccnz .LBB0_289
	v_mov_b32_e32 v1, v169
	v_sub_f32_e32 v3, 1.0, v1
	v_fmac_f32_e32 v1, v2, v3
	v_sub_f32_e32 v23, 1.0, v1

; __device__ __forceinline__ float bf_lo(unsigned u) { return __uint_as_float(u << 16); }
; __device__ __forceinline__ float bf_hi(unsigned u) { return __uint_as_float(u & 0xffff0000u); }
; __device__ __forceinline__ float fast_rcp(float x) { return __builtin_amdgcn_rcpf(x); }
; __device__ void prep_item(const Params& p, int l, int item, LAS unsigned char* lds) {
;     ...
;         for (int j = 0; j < 8; ++j) {
;             const unsigned fw = f[j >> 1]; const float x = (j & 1) ? bf_hi(fw) : bf_lo(fw);
;             const float e = __expf(-fabsf(x)), r = fast_rcp(1.0f + e);
;             const float sp = x >= 0.f ? r : e * r, sn = x >= 0.f ? e * r : r;
;             if (first) { E[j] = sp; kk[j] = sn; }
;             else { const float lb = lbp[j]; const float gate = lb + (1.0f - lb) * sp; E[j] = gate; kk[j] = 1.0f - gate; }
.LBB0_291:
	s_andn2_b64 vcc, exec, s[40:41]
	s_cbranch_vccnz .LBB0_293
	v_mov_b32_e32 v2, v170
	v_sub_f32_e32 v4, 1.0, v2
	v_fmac_f32_e32 v2, v3, v4
	v_sub_f32_e32 v18, 1.0, v2

; __device__ __forceinline__ float bf_lo(unsigned u) { return __uint_as_float(u << 16); }
; __device__ __forceinline__ float bf_hi(unsigned u) { return __uint_as_float(u & 0xffff0000u); }
; __device__ __forceinline__ float fast_rcp(float x) { return __builtin_amdgcn_rcpf(x); }
; __device__ void prep_item(const Params& p, int l, int item, LAS unsigned char* lds) {
;     ...
;         for (int j = 0; j < 8; ++j) {
;             const unsigned fw = f[j >> 1]; const float x = (j & 1) ? bf_hi(fw) : bf_lo(fw);
;             const float e = __expf(-fabsf(x)), r = fast_rcp(1.0f + e);
;             const float sp = x >= 0.f ? r : e * r, sn = x >= 0.f ? e * r : r;
;             if (first) { E[j] = sp; kk[j] = sn; }
;             else { const float lb = lbp[j]; const float gate = lb + (1.0f - lb) * sp; E[j] = gate; kk[j] = 1.0f - gate; }
.LBB0_295:
	s_andn2_b64 vcc, exec, s[40:41]
	s_cbranch_vccnz .LBB0_297
	v_mov_b32_e32 v3, v171
	v_sub_f32_e32 v5, 1.0, v3
	v_fmac_f32_e32 v3, v4, v5
	v_sub_f32_e32 v19, 1.0, v3

; __device__ __forceinline__ float bf_lo(unsigned u) { return __uint_as_float(u << 16); }
; __device__ __forceinline__ float bf_hi(unsigned u) { return __uint_as_float(u & 0xffff0000u); }
; __device__ __forceinline__ float fast_rcp(float x) { return __builtin_amdgcn_rcpf(x); }
; __device__ void prep_item(const Params& p, int l, int item, LAS unsigned char* lds) {
;     ...
;         for (int j = 0; j < 8; ++j) {
;             const unsigned fw = f[j >> 1]; const float x = (j & 1) ? bf_hi(fw) : bf_lo(fw);
;             const float e = __expf(-fabsf(x)), r = fast_rcp(1.0f + e);
;             const float sp = x >= 0.f ? r : e * r, sn = x >= 0.f ? e * r : r;
;             if (first) { E[j] = sp; kk[j] = sn; }
;             else { const float lb = lbp[j]; const float gate = lb + (1.0f - lb) * sp; E[j] = gate; kk[j] = 1.0f - gate; }
.LBB0_299:
	s_andn2_b64 vcc, exec, s[40:41]
	s_cbranch_vccnz .LBB0_301
	v_mov_b32_e32 v4, v172
	v_sub_f32_e32 v6, 1.0, v4
	v_fmac_f32_e32 v4, v5, v6
	v_sub_f32_e32 v24, 1.0, v4

; __device__ __forceinline__ float bf_lo(unsigned u) { return __uint_as_float(u << 16); }
; __device__ __forceinline__ float bf_hi(unsigned u) { return __uint_as_float(u & 0xffff0000u); }
; __device__ __forceinline__ float fast_rcp(float x) { return __builtin_amdgcn_rcpf(x); }
; __device__ void prep_item(const Params& p, int l, int item, LAS unsigned char* lds) {
;     ...
;         for (int j = 0; j < 8; ++j) {
;             const unsigned fw = f[j >> 1]; const float x = (j & 1) ? bf_hi(fw) : bf_lo(fw);
;             const float e = __expf(-fabsf(x)), r = fast_rcp(1.0f + e);
;             const float sp = x >= 0.f ? r : e * r, sn = x >= 0.f ? e * r : r;
;             if (first) { E[j] = sp; kk[j] = sn; }
;             else { const float lb = lbp[j]; const float gate = lb + (1.0f - lb) * sp; E[j] = gate; kk[j] = 1.0f - gate; }
.LBB0_303:
	s_andn2_b64 vcc, exec, s[40:41]
	s_cbranch_vccnz .LBB0_305
	v_mov_b32_e32 v5, v173
	v_sub_f32_e32 v7, 1.0, v5
	v_fmac_f32_e32 v5, v6, v7
	v_sub_f32_e32 v25, 1.0, v5

; __device__ __forceinline__ float bf_lo(unsigned u) { return __uint_as_float(u << 16); }
; __device__ __forceinline__ float bf_hi(unsigned u) { return __uint_as_float(u & 0xffff0000u); }
; __device__ __forceinline__ float fast_rcp(float x) { return __builtin_amdgcn_rcpf(x); }
; __device__ void prep_item(const Params& p, int l, int item, LAS unsigned char* lds) {
;     ...
;         for (int j = 0; j < 8; ++j) {
;             const unsigned fw = f[j >> 1]; const float x = (j & 1) ? bf_hi(fw) : bf_lo(fw);
;             const float e = __expf(-fabsf(x)), r = fast_rcp(1.0f + e);
;             const float sp = x >= 0.f ? r : e * r, sn = x >= 0.f ? e * r : r;
;             if (first) { E[j] = sp; kk[j] = sn; }
;             else { const float lb = lbp[j]; const float gate = lb + (1.0f - lb) * sp; E[j] = gate; kk[j] = 1.0f - gate; }
.LBB0_307:
	s_andn2_b64 vcc, exec, s[40:41]
	s_cbranch_vccnz .LBB0_309
	v_mov_b32_e32 v6, v174
	v_sub_f32_e32 v20, 1.0, v6
	v_fmac_f32_e32 v6, v7, v20
	v_sub_f32_e32 v20, 1.0, v6

; __device__ __forceinline__ float bf_lo(unsigned u) { return __uint_as_float(u << 16); }
; __device__ __forceinline__ float bf_hi(unsigned u) { return __uint_as_float(u & 0xffff0000u); }
; __device__ __forceinline__ float fast_rcp(float x) { return __builtin_amdgcn_rcpf(x); }
; __device__ void prep_item(const Params& p, int l, int item, LAS unsigned char* lds) {
;     ...
;         for (int j = 0; j < 8; ++j) {
;             const unsigned fw = f[j >> 1]; const float x = (j & 1) ? bf_hi(fw) : bf_lo(fw);
;             const float e = __expf(-fabsf(x)), r = fast_rcp(1.0f + e);
;             const float sp = x >= 0.f ? r : e * r, sn = x >= 0.f ? e * r : r;
;             if (first) { E[j] = sp; kk[j] = sn; }
;             else { const float lb = lbp[j]; const float gate = lb + (1.0f - lb) * sp; E[j] = gate; kk[j] = 1.0f - gate; }
.LBB0_311:
	s_andn2_b64 vcc, exec, s[40:41]
	s_cbranch_vccnz .LBB0_313
	v_mov_b32_e32 v7, v175
	v_sub_f32_e32 v21, 1.0, v7
	v_fmac_f32_e32 v7, v29, v21
	v_sub_f32_e32 v21, 1.0, v7

; #define LAS __attribute__((address_space(3)))
; __device__ __forceinline__ size_t PIX(int row, int col) { return (size_t)(col >> 7) * PSLOT + (size_t)row * 128 + (col & 127); }
; __device__ __forceinline__ float bf_lo(unsigned u) { return __uint_as_float(u << 16); }
; __device__ void prep_item(const Params& p, int l, int item, LAS unsigned char* lds) {
;     ...
;         float qt[8], kh_[8], kt_[8], Tj[8];
;         cumprod32x8(E);
; #pragma unroll
;         for (int j = 0; j < 8; ++j) {
;             const float Ej = fmaxf(E[j], 1e-35f);
;             const float T0 = __builtin_bit_cast(float, __builtin_amdgcn_readlane(__builtin_bit_cast(int, Ej), 31)), T1 = __builtin_bit_cast(float, __builtin_amdgcn_readlane(__builtin_bit_cast(int, Ej), 63));
;             const float T = kh ? T1 : T0;
;             const unsigned qw = q[j >> 1]; const float qx = (j & 1) ? bf_hi(qw) : bf_lo(qw);
;             qt[j] = silu_f(qx) * 0.08838834764831845f * Ej;
;             kh_[j] = kk[j] * fast_rcp(Ej); kt_[j] = kh_[j] * T;
;             Tj[j] = T;
;         }
;         if (tau == 31) { float* dp = (float*)(p.ws + WS_DS) + ((size_t)((b * 4 + h) * 2 + dir) * NCH + ci) * 128 + k0;
;             *(f32x4*)dp = (f32x4){Tj[0], Tj[1], Tj[2], Tj[3]}; *(f32x4*)(dp + 4) = (f32x4){Tj[4], Tj[5], Tj[6], Tj[7]}; }
;         u32x4 wq, wk; wq.x = pk_bf16(qt[0], qt[1]); wq.y = pk_bf16(qt[2], qt[3]); wq.z = pk_bf16(qt[4], qt[5]); wq.w = pk_bf16(qt[6], qt[7]);
;         wk.x = pk_bf16(kh_[0], kh_[1]); wk.y = pk_bf16(kh_[2], kh_[3]); wk.z = pk_bf16(kh_[4], kh_[5]); wk.w = pk_bf16(kh_[6], kh_[7]);
;         *(LAS u32x4*)(Qs + tau * QS_ST + k0) = wq; *(LAS u32x4*)(Kh + tau * QS_ST + k0) = wk;
;         {
;           bf16_t* qd = (dir == 0) ? P + PIX(R0 + tokl, 1536 + h * 128) : (bf16_t*)(p.ws + WS_QB) + (size_t)h * PSLOT + (size_t)(R0 + tokl) * 128;
;           const int a32 = k0 & ~31, kkA = k0 & 31, kkB = kkA + 4;
;           u32x2 pa, pb; pa.x = wq.x; pa.y = wq.y; pb.x = wq.z; pb.y = wq.w;
;           *(u32x2*)(qd + a32 + 8 * ((kkA & 15) >> 2) + 4 * (kkA >> 4)) = pa;
;           *(u32x2*)(qd + a32 + 8 * ((kkB & 15) >> 2) + 4 * (kkB >> 4)) = pb; }
; #pragma unroll
;         for (int j = 0; j < 8; ++j) { Kt[(k0 + j) * KT_ST + tokl] = to_bf1(kt_[j]); const unsigned vw = v[j >> 1]; Vt[(k0 + j) * KT_ST + tau] = (bf16_t)((j & 1) ? (vw >> 16) : (vw & 0xffffu)); }
.LBB0_315:
	s_or_b64 exec, exec, s[0:1]
	v_lshlrev_b32_e32 v34, 16, v14
	v_and_b32_e32 v35, 0xffff0000, v14
	v_mul_f32_e32 v14, 0xbfb8aa3b, v34
	v_exp_f32_e32 v14, v14
	v_rcp_f32_e32 v50, v44
	v_rcp_f32_e32 v51, v45
	s_cmp_gt_u32 s73, 7
	v_add_f32_e32 v14, 1.0, v14
	v_rcp_f32_e32 v52, v14
	v_mul_f32_e32 v14, 0xbfb8aa3b, v35
	v_exp_f32_e32 v14, v14
	v_pk_mul_f32 v[22:23], v[22:23], v[50:51]
	v_readlane_b32 s6, v240, 28
	s_cselect_b64 s[0:1], -1, 0
	v_add_f32_e32 v14, 1.0, v14
	v_rcp_f32_e32 v53, v14
	v_rcp_f32_e32 v14, v42
	v_readlane_b32 s7, v240, 29
	v_mul_u32_u24_e32 v29, 0x110, v31
	v_pk_mul_f32 v[34:35], v[52:53], v[34:35]
	s_or_b64 s[6:7], s[6:7], s[0:1]
	v_pk_mul_f32 v[34:35], v[34:35], s[86:87] op_sel_hi:[1,0]
	v_readlane_b32 s0, v240, 19
	v_pk_mul_f32 v[34:35], v[34:35], v[44:45]
	v_lshlrev_b32_e32 v44, 16, v15
	v_and_b32_e32 v45, 0xffff0000, v15
	v_mul_f32_e32 v15, 0xbfb8aa3b, v44
	v_exp_f32_e32 v15, v15
	v_add3_u32 v29, s0, v29, v46
	s_mul_i32 s0, s74, 0x880000
	v_readlane_b32 s1, v242, 6
	v_add_f32_e32 v15, 1.0, v15
	v_rcp_f32_e32 v50, v15
	v_mul_f32_e32 v15, 0xbfb8aa3b, v45
	v_exp_f32_e32 v15, v15
	s_add_u32 s8, s1, s0
	v_readlane_b32 s1, v242, 7
	s_addc_u32 s9, s1, 0
	v_add_f32_e32 v15, 1.0, v15
	v_rcp_f32_e32 v51, v15
	v_rcp_f32_e32 v15, v43
	v_lshl_add_u64 v[32:33], s[8:9], 0, v[32:33]
	v_mov_b32_e32 v37, v8
	v_pk_mul_f32 v[44:45], v[50:51], v[44:45]
	v_readlane_b32 s1, v242, 60
	v_pk_mul_f32 v[44:45], v[44:45], s[86:87] op_sel_hi:[1,0]
	s_andn2_b64 vcc, exec, s[6:7]
	v_pk_mul_f32 v[44:45], v[44:45], v[42:43]
	v_pk_mul_f32 v[42:43], v[18:19], v[14:15]
	v_lshlrev_b32_e32 v18, 16, v16
	v_mul_f32_e32 v15, 0xbfb8aa3b, v18
	v_exp_f32_e32 v15, v15
	v_and_b32_e32 v19, 0xffff0000, v16
	v_rcp_f32_e32 v14, v40
	v_lshlrev_b32_e32 v16, 16, v17
	v_add_f32_e32 v15, 1.0, v15
	v_rcp_f32_e32 v50, v15
	v_mul_f32_e32 v15, 0xbfb8aa3b, v19
	v_exp_f32_e32 v15, v15
	v_and_b32_e32 v17, 0xffff0000, v17
	v_mul_f32_e32 v2, v42, v2
	v_mul_f32_e32 v3, v43, v3
	v_add_f32_e32 v15, 1.0, v15
	v_rcp_f32_e32 v51, v15
	v_rcp_f32_e32 v15, v41
	v_cvt_pk_bf16_f32 v2, v2, s0
	v_pk_mul_f32 v[18:19], v[50:51], v[18:19]
	v_pk_mul_f32 v[24:25], v[24:25], v[14:15]
	v_mul_f32_e32 v15, 0xbfb8aa3b, v16
	v_exp_f32_e32 v15, v15
	v_pk_mul_f32 v[18:19], v[18:19], s[86:87] op_sel_hi:[1,0]
	v_rcp_f32_e32 v14, v38
	v_pk_mul_f32 v[18:19], v[18:19], v[40:41]
	v_add_f32_e32 v15, 1.0, v15
	v_rcp_f32_e32 v40, v15
	v_mul_f32_e32 v15, 0xbfb8aa3b, v17
	v_exp_f32_e32 v15, v15
	v_cvt_pk_bf16_f32 v18, v18, v19
	v_mul_f32_e32 v4, v24, v4
	v_mul_f32_e32 v5, v25, v5
	v_add_f32_e32 v15, 1.0, v15
	v_rcp_f32_e32 v41, v15
	v_rcp_f32_e32 v15, v39
	v_pk_mul_f32 v[16:17], v[40:41], v[16:17]
	s_nop 0
	v_pk_mul_f32 v[16:17], v[16:17], s[86:87] op_sel_hi:[1,0]
	v_pk_mul_f32 v[20:21], v[20:21], v[14:15]
	v_pk_mul_f32 v[40:41], v[16:17], v[38:39]
	v_cvt_pk_bf16_f32 v38, v22, v23
	v_cvt_pk_bf16_f32 v19, v40, v41
	v_cvt_pk_bf16_f32 v39, v42, v43
	v_cvt_pk_bf16_f32 v40, v24, v25
	v_cvt_pk_bf16_f32 v41, v20, v21
	ds_write_b128 v29, v[38:41]
	v_mul_f32_e32 v7, v21, v7
	v_mul_f32_e32 v6, v20, v6
	v_mul_f32_e32 v20, v23, v1
	v_mul_f32_e32 v21, v22, v0
	v_lshl_add_u64 v[0:1], v[26:27], 1, v[32:33]
	v_mov_b32_e32 v29, v8
	v_lshl_add_u64 v[0:1], v[0:1], 0, v[28:29]
	v_cvt_pk_bf16_f32 v16, v34, v35
	v_cvt_pk_bf16_f32 v17, v44, v45
	v_lshl_add_u64 v[0:1], v[0:1], 0, v[36:37]
	ds_write_b128 v47, v[16:19] offset:58368
	global_store_dwordx2 v[0:1], v[16:17], off
	global_store_dwordx2 v[0:1], v[18:19], off offset:16
	v_lshlrev_b32_e32 v0, 1, v56
	v_lshlrev_b32_e32 v1, 1, v31
	v_cvt_pk_bf16_f32 v16, v21, s0
	v_add3_u32 v0, s1, v0, v48
	v_readlane_b32 s1, v240, 20
	ds_write_b16 v0, v16
	v_cvt_pk_bf16_f32 v16, v20, s0
	v_add3_u32 v1, s1, v1, v48
	ds_write_b16 v1, v10
	ds_write_b16 v0, v16 offset:80
	ds_write_b16_d16_hi v1, v10 offset:80
	ds_write_b16 v0, v2 offset:160
	ds_write_b16 v1, v11 offset:160
	v_cvt_pk_bf16_f32 v2, v3, s0
	ds_write_b16 v0, v2 offset:240
	ds_write_b16_d16_hi v1, v11 offset:240
	v_cvt_pk_bf16_f32 v2, v4, s0
	ds_write_b16 v0, v2 offset:320
	ds_write_b16 v1, v12 offset:320
	v_cvt_pk_bf16_f32 v2, v5, s0
	ds_write_b16 v0, v2 offset:400
	ds_write_b16_d16_hi v1, v12 offset:400
	v_cvt_pk_bf16_f32 v2, v6, s0
	v_and_b32_e32 v14, 15, v54
	v_lshrrev_b32_e32 v15, 4, v57
	ds_write_b16 v0, v2 offset:480
	ds_write_b16 v1, v13 offset:480
	v_cvt_pk_bf16_f32 v2, v7, s0
	ds_write_b16 v0, v2 offset:560
	ds_write_b16_d16_hi v1, v13 offset:560
	v_cndmask_b32_e64 v0, 0, 1, s[6:7]
	v_mul_u32_u24_e32 v1, 0x88, v14
	v_lshlrev_b32_e32 v18, 2, v15
	v_or_b32_e32 v2, v30, v14
	s_movk_i32 s1, 0x50
	v_cmp_ne_u32_e64 s[38:39], 1, v0
	v_lshlrev_b32_e32 v0, 3, v15
	v_lshlrev_b32_e32 v19, 4, v15
	v_lshlrev_b32_e32 v10, 1, v14
	v_mul_u32_u24_e32 v17, 0x140, v15
	v_and_b32_e32 v6, 48, v54
	v_mul_u32_u24_e32 v7, 0x50, v14
	v_ashrrev_i32_e32 v31, 31, v30
	v_lshlrev_b32_e32 v22, 1, v1
	v_cmp_gt_u32_e64 s[40:41], v14, v18
	v_or_b32_e32 v12, 1, v18
	v_or_b32_e32 v16, 2, v18
	v_or_b32_e32 v13, 3, v18
	v_mul_lo_u32 v11, v2, s1
	s_add_u32 s20, s85, s22
	v_readlane_b32 s21, v243, 43
	s_nop 1
	s_addc_u32 s21, s21, 0
	s_nop 4
	global_load_dwordx4 v[156:159], v214, s[20:21]
	global_load_dwordx4 v[160:163], v214, s[20:21] offset:16
	global_load_dwordx4 v[168:171], v214, s[20:21] offset:2048
	global_load_dwordx4 v[172:175], v214, s[20:21] offset:2064
	s_waitcnt lgkmcnt(0)
	s_barrier
; #define LAS __attribute__((address_space(3)))
; __device__ __forceinline__ unsigned pk_bf16(float a, float b) { f32x2 v = {a, b}; bf2_t r = __builtin_convertvector(v, bf2_t); return __builtin_bit_cast(unsigned, r); }
; __device__ __forceinline__ bf16_t to_bf1(float a) { return (bf16_t)(pk_bf16(a, 0.f) & 0xffffu); }
; __device__ void prep_item(const Params& p, int l, int item, LAS unsigned char* lds) {
;     ...
;         if (want_out) {
;             f32x4 a00 = (f32x4){0.f, 0.f, 0.f, 0.f}, a10 = a00, a11 = a00;
; #pragma unroll
;             for (int kb = 0; kb < 4; ++kb) {
;                 const bf16x8 qn0 = *(const LAS bf16x8*)(Qs + l15 * QS_ST + 32 * kb + 8 * q4), qn1 = *(const LAS bf16x8*)(Qs + (16 + l15) * QS_ST + 32 * kb + 8 * q4);
;                 const bf16x8 kh0 = *(const LAS bf16x8*)(Kh + l15 * QS_ST + 32 * kb + 8 * q4), kh1 = *(const LAS bf16x8*)(Kh + (16 + l15) * QS_ST + 32 * kb + 8 * q4);
;                 a00 = __builtin_amdgcn_mfma_f32_16x16x32_bf16(qn0, kh0, a00, 0, 0, 0);
;                 a10 = __builtin_amdgcn_mfma_f32_16x16x32_bf16(qn1, kh0, a10, 0, 0, 0);
;                 a11 = __builtin_amdgcn_mfma_f32_16x16x32_bf16(qn1, kh1, a11, 0, 0, 0);
;             }
; #pragma unroll
;             for (int i = 0; i < 4; ++i) { const int t = 4 * q4 + i; const bool keep = l15 <= t;
;                 Aw[t * KT_ST + l15] = to_bf1(keep ? a00[i] : 0.f);
;                 Aw[(16 + t) * KT_ST + l15] = to_bf1(a10[i]);
;                 Aw[(16 + t) * KT_ST + 16 + l15] = to_bf1(keep ? a11[i] : 0.f); }
;             asm volatile("s_waitcnt lgkmcnt(0)" ::: "memory");
;             const bf16x8 vf = *(const LAS bf16x8*)(Vt + (16 * w + l15) * KT_ST + 8 * q4);
;             bf16_t* OFB = (bf16_t*)(p.ws + WS_OFB) + (size_t)dir * NROW * 512;
; #pragma unroll
;             for (int mt = 0; mt < 2; ++mt) {
;                 const bf16x8 af = *(const LAS bf16x8*)(Aw + (16 * mt + l15) * KT_ST + 8 * q4);
;                 const f32x4 o = __builtin_amdgcn_mfma_f32_16x16x32_bf16(vf, af, (f32x4){0.f, 0.f, 0.f, 0.f}, 0, 0, 0);
;                 const int tl = 16 * mt + l15, tok = dir ? 31 - tl : tl;
;                 u32x2 wv; wv.x = pk_bf16(o[0], o[1]); wv.y = pk_bf16(o[2], o[3]);
;                 *(u32x2*)(OFB + (size_t)h * PSLOT + (size_t)(R0 + tok) * 128 + 16 * w + 4 * q4) = wv;
;             }
	s_cbranch_vccnz .LBB0_317
	v_add3_u32 v1, 16, v22, v19
	ds_read_b128 v[2:5], v1
	ds_read_b128 v[24:27], v1 offset:4352
	ds_read_b128 v[32:35], v1 offset:8704
	ds_read_b128 v[36:39], v1 offset:13056
	s_movk_i32 s1, 0x140
	v_cmp_gt_u32_e32 vcc, v14, v12
	v_add3_u32 v23, v55, v7, v6
	s_waitcnt lgkmcnt(1)
	v_mfma_f32_16x16x32_bf16 v[2:5], v[2:5], v[32:35], 0
	v_readlane_b32 s6, v242, 8
	v_readlane_b32 s7, v242, 9
	s_add_u32 s6, s6, s0
	v_mfma_f32_16x16x32_bf16 v[32:35], v[24:27], v[32:35], 0
	v_add_u32_e32 v28, s70, v14
	v_mov_b32_e32 v29, v8
	s_addc_u32 s7, s7, 0
	s_waitcnt lgkmcnt(0)
	v_mfma_f32_16x16x32_bf16 v[24:27], v[24:27], v[36:39], 0
	ds_read_b128 v[36:39], v1 offset:64
	ds_read_b128 v[40:43], v1 offset:4416
	ds_read_b128 v[44:47], v1 offset:8768
	ds_read_b128 v[48:51], v1 offset:13120
	s_waitcnt lgkmcnt(1)
	v_mfma_f32_16x16x32_bf16 v[2:5], v[36:39], v[44:47], v[2:5]
	v_mfma_f32_16x16x32_bf16 v[32:35], v[40:43], v[44:47], v[32:35]
	s_waitcnt lgkmcnt(0)
	v_mfma_f32_16x16x32_bf16 v[24:27], v[40:43], v[48:51], v[24:27]
	ds_read_b128 v[36:39], v1 offset:128
	ds_read_b128 v[40:43], v1 offset:4480
	ds_read_b128 v[44:47], v1 offset:8832
	ds_read_b128 v[48:51], v1 offset:13184
	s_waitcnt lgkmcnt(1)
	v_mfma_f32_16x16x32_bf16 v[2:5], v[36:39], v[44:47], v[2:5]
	v_mfma_f32_16x16x32_bf16 v[32:35], v[40:43], v[44:47], v[32:35]
	s_waitcnt lgkmcnt(0)
	v_mfma_f32_16x16x32_bf16 v[24:27], v[40:43], v[48:51], v[24:27]
	ds_read_b128 v[36:39], v1 offset:192
	ds_read_b128 v[40:43], v1 offset:4544
	ds_read_b128 v[44:47], v1 offset:8896
	ds_read_b128 v[48:51], v1 offset:13248
	v_add_u32_e32 v1, v55, v10
	v_mad_u32_u24 v20, v15, s1, v1
	s_waitcnt lgkmcnt(1)
	v_mfma_f32_16x16x32_bf16 v[2:5], v[36:39], v[44:47], v[2:5]
	s_movk_i32 s1, 0x50
	v_mfma_f32_16x16x32_bf16 v[32:35], v[40:43], v[44:47], v[32:35]
	s_nop 5
	v_cvt_pk_bf16_f32 v2, v2, s0
	v_cndmask_b32_e64 v2, v2, 0, s[40:41]
	ds_write_b16 v20, v2 offset:37888
	s_waitcnt lgkmcnt(1)
	v_mfma_f32_16x16x32_bf16 v[24:27], v[40:43], v[48:51], v[24:27]
	v_add3_u32 v20, v55, v17, v10
	v_cvt_pk_bf16_f32 v2, v32, s0
	ds_write_b16 v20, v2 offset:39168
	s_nop 4
	v_cvt_pk_bf16_f32 v2, v24, s0
	v_cndmask_b32_e64 v2, v2, 0, s[40:41]
	ds_write_b16 v20, v2 offset:39200
	v_cvt_pk_bf16_f32 v2, v3, s0
	v_cndmask_b32_e64 v2, v2, 0, vcc
	v_mul_u32_u24_e32 v3, 0x50, v12
	v_mad_u32_u24 v20, v12, s1, v1
	ds_write_b16 v20, v2 offset:37888
	v_cvt_pk_bf16_f32 v2, v33, s0
	v_add3_u32 v3, v55, v3, v10
	ds_write_b16 v3, v2 offset:39168
	v_cvt_pk_bf16_f32 v2, v25, s0
	v_cndmask_b32_e64 v2, v2, 0, vcc
	ds_write_b16 v3, v2 offset:39200
	v_cmp_gt_u32_e32 vcc, v14, v16
	v_cvt_pk_bf16_f32 v2, v4, s0
	v_mad_u32_u24 v3, v12, s1, s1
	v_cndmask_b32_e64 v2, v2, 0, vcc
	v_add_u32_e32 v4, v1, v3
	ds_write_b16 v4, v2 offset:37888
	v_cvt_pk_bf16_f32 v2, v34, s0
	v_add3_u32 v3, v55, v3, v10
	ds_write_b16 v3, v2 offset:39168
	v_cvt_pk_bf16_f32 v2, v26, s0
	v_cndmask_b32_e64 v2, v2, 0, vcc
	ds_write_b16 v3, v2 offset:39200
	v_cmp_gt_u32_e32 vcc, v14, v13
	v_cvt_pk_bf16_f32 v2, v5, s0
	v_mad_u32_u24 v3, v12, s1, v186
	v_cndmask_b32_e64 v2, v2, 0, vcc
	v_add_u32_e32 v1, v1, v3
	ds_write_b16 v1, v2 offset:37888
	v_cvt_pk_bf16_f32 v1, v35, s0
	v_add3_u32 v2, v55, v3, v10
	ds_write_b16 v2, v1 offset:39168
	v_cvt_pk_bf16_f32 v1, v27, s0
	v_cndmask_b32_e64 v1, v1, 0, vcc
	ds_write_b16 v2, v1 offset:39200
	s_waitcnt lgkmcnt(0)
	v_add3_u32 v1, 16, v11, v6
	ds_read_b128 v[2:5], v1 offset:17408
	ds_read_b128 v[24:27], v23 offset:37888
	s_waitcnt lgkmcnt(0)
	v_mfma_f32_16x16x32_bf16 v[24:27], v[2:5], v[24:27], 0
	v_lshlrev_b64 v[32:33], 1, v[30:31]
	v_mov_b32_e32 v1, v8
	s_nop 5
	v_cvt_pk_bf16_f32 v20, v24, v25
	v_lshlrev_b64 v[24:25], 8, v[28:29]
	v_lshl_add_u64 v[24:25], s[6:7], 0, v[24:25]
	v_lshl_add_u64 v[24:25], v[24:25], 0, v[32:33]
	v_cvt_pk_bf16_f32 v21, v26, v27
	v_lshl_add_u64 v[24:25], v[24:25], 0, v[0:1]
	global_store_dwordx2 v[24:25], v[20:21], off
	ds_read_b128 v[24:27], v23 offset:39168
	s_waitcnt lgkmcnt(0)
	v_mfma_f32_16x16x32_bf16 v[2:5], v[2:5], v[24:27], 0
	s_nop 7
	v_cvt_pk_bf16_f32 v2, v2, v3
	v_cvt_pk_bf16_f32 v3, v4, v5
	v_add_u32_e32 v4, 16, v28
	v_mov_b32_e32 v5, v8
	v_lshlrev_b64 v[4:5], 8, v[4:5]
	v_lshl_add_u64 v[4:5], s[6:7], 0, v[4:5]
	v_lshl_add_u64 v[4:5], v[4:5], 0, v[32:33]
	v_lshl_add_u64 v[4:5], v[4:5], 0, v[0:1]
	global_store_dwordx2 v[4:5], v[2:3], off

; __global__ void __launch_bounds__(512, 2) fwd_megakernel(Params p) {
	.amdhsa_kernel _Z14fwd_megakernel6Params
		.amdhsa_group_segment_fixed_size 16
		.amdhsa_private_segment_fixed_size 0
		.amdhsa_kernarg_size 448
		.amdhsa_user_sgpr_count 2
		.amdhsa_user_sgpr_dispatch_ptr 0
		.amdhsa_user_sgpr_queue_ptr 0
		.amdhsa_user_sgpr_kernarg_segment_ptr 1
		.amdhsa_user_sgpr_dispatch_id 0
		.amdhsa_user_sgpr_kernarg_preload_length 0
		.amdhsa_user_sgpr_kernarg_preload_offset 0
		.amdhsa_user_sgpr_private_segment_size 0
		.amdhsa_uses_dynamic_stack 0
		.amdhsa_enable_private_segment 0
		.amdhsa_system_sgpr_workgroup_id_x 1
		.amdhsa_system_sgpr_workgroup_id_y 0
		.amdhsa_system_sgpr_workgroup_id_z 0
		.amdhsa_system_sgpr_workgroup_info 0
		.amdhsa_system_vgpr_workitem_id 2
		.amdhsa_next_free_vgpr 245
		.amdhsa_next_free_sgpr 102
		.amdhsa_accum_offset 248
		.amdhsa_reserve_vcc 1
		.amdhsa_float_round_mode_32 0
		.amdhsa_float_round_mode_16_64 0
		.amdhsa_float_denorm_mode_32 3
		.amdhsa_float_denorm_mode_16_64 3
		.amdhsa_dx10_clamp 1
		.amdhsa_ieee_mode 1
		.amdhsa_fp16_overflow 0
		.amdhsa_tg_split 0
		.amdhsa_exception_fp_ieee_invalid_op 0
		.amdhsa_exception_fp_denorm_src 0
		.amdhsa_exception_fp_ieee_div_zero 0
		.amdhsa_exception_fp_ieee_overflow 0
		.amdhsa_exception_fp_ieee_underflow 0
		.amdhsa_exception_fp_ieee_inexact 0
		.amdhsa_exception_int_div_zero 0
	.end_amdhsa_kernel

; __global__ void __launch_bounds__(512, 2) fwd_megakernel(Params p) {
amdhsa.kernels:
  - .agpr_count:     0
    .args:
      - .offset:         0
        .size:           192
        .value_kind:     by_value
      - .offset:         192
        .size:           4
        .value_kind:     hidden_block_count_x
      - .offset:         196
        .size:           4
        .value_kind:     hidden_block_count_y
      - .offset:         200
        .size:           4
        .value_kind:     hidden_block_count_z
      - .offset:         204
        .size:           2
        .value_kind:     hidden_group_size_x
      - .offset:         206
        .size:           2
        .value_kind:     hidden_group_size_y
      - .offset:         208
        .size:           2
        .value_kind:     hidden_group_size_z
      - .offset:         210
        .size:           2
        .value_kind:     hidden_remainder_x
      - .offset:         212
        .size:           2
        .value_kind:     hidden_remainder_y
      - .offset:         214
        .size:           2
        .value_kind:     hidden_remainder_z
      - .offset:         232
        .size:           8
        .value_kind:     hidden_global_offset_x
      - .offset:         240
        .size:           8
        .value_kind:     hidden_global_offset_y
      - .offset:         248
        .size:           8
        .value_kind:     hidden_global_offset_z
      - .offset:         256
        .size:           2
        .value_kind:     hidden_grid_dims
      - .offset:         280
        .size:           8
        .value_kind:     hidden_multigrid_sync_arg
      - .offset:         312
        .size:           4
        .value_kind:     hidden_dynamic_lds_size
    .group_segment_fixed_size: 16
    .kernarg_segment_align: 8
    .kernarg_segment_size: 448
    .language:       OpenCL C
    .language_version:
      - 2
      - 0
    .max_flat_workgroup_size: 512
    .name:           _Z14fwd_megakernel6Params
    .private_segment_fixed_size: 0
    .sgpr_count:     108
    .sgpr_spill_count: 297
    .symbol:         _Z14fwd_megakernel6Params.kd
    .uniform_work_group_size: 1
    .uses_dynamic_stack: false
    .vgpr_count:     245
    .vgpr_spill_count: 0
    .wavefront_size: 64
